# D loops: bias-change test computed before the row-max chain; A/D loops: two-chain row max, dead uniform-branch pairs removed
# speedup vs baseline: 1.0018x; 1.0018x over previous
; template <int MODE, bool FIRST, bool FOLD>
; __device__ __forceinline__ bool partialSM(f32x16& p0, f32x16& p1, float& m_reg, float& alpha, int relbase, bool near, const float* lut, float cb) {
;     ...
;     float pmax = p0[0];
; #pragma unroll
;     for (int r = 1; r < 16; ++r) pmax = fmaxf(pmax, p0[r]);
; #pragma unroll
;     for (int r = 0; r < 16; ++r) pmax = fmaxf(pmax, p1[r]);
;     { auto rr = __builtin_amdgcn_permlane32_swap(__float_as_uint(pmax), __float_as_uint(pmax), false, false);
;       pmax = fmaxf(__uint_as_float(rr[0]), __uint_as_float(rr[1])); }
;     bool resc;
;     if (FIRST && MODE != 2) resc = true; else resc = __any(pmax > THR2);
;     if (__builtin_expect(resc, FIRST && MODE != 2)) {
;         const float delta = (FIRST && MODE != 2) ? pmax : fmaxf(pmax, 0.f);
;         m_reg += delta; alpha = (FIRST && MODE != 2) ? 1.f : __builtin_amdgcn_exp2f(-delta);
; #pragma unroll
;         for (int r = 0; r < 16; ++r) { p0[r] -= delta; p1[r] -= delta; }
;     } else alpha = 1.f;
; #pragma unroll
;     for (int r = 0; r < 16; ++r) p0[r] = __builtin_amdgcn_exp2f(p0[r]);
;     return resc;
; template <int S, bool RSM> __device__ __forceinline__ void fsm_step(f32x16& pc0, f32x16& pc1, float& ps, float& l_reg, bf16x8& pa0, bf16x8& pa1, bf16x8& pa2, bf16x8& pa3) {
;     if (S < 4) {
; #pragma unroll
;         for (int r = 0; r < 4; ++r) pc1[4 * S + r] = __builtin_amdgcn_exp2f(pc1[4 * S + r]); }
;     if (S == 4) { PK4X(pc0, 0, pa0); if (!RSM) ps = ((pc0[0] + pc0[1]) + (pc0[2] + pc0[3])) + ((pc0[4] + pc0[5]) + (pc0[6] + pc0[7])); }
;     if (S == 5) { PK4X(pc0, 8, pa1); if (!RSM) ps += ((pc0[8] + pc0[9]) + (pc0[10] + pc0[11])) + ((pc0[12] + pc0[13]) + (pc0[14] + pc0[15])); }
;     if (S == 6) { PK4X(pc1, 0, pa2); if (!RSM) ps += ((pc1[0] + pc1[1]) + (pc1[2] + pc1[3])) + ((pc1[4] + pc1[5]) + (pc1[6] + pc1[7])); }
;     if (S == 7 && RSM) PK4X(pc1, 8, pa3);
;     if (S == 7 && !RSM) { PK4X(pc1, 8, pa3); ps += ((pc1[8] + pc1[9]) + (pc1[10] + pc1[11])) + ((pc1[12] + pc1[13]) + (pc1[14] + pc1[15]));
;         auto rr = __builtin_amdgcn_permlane32_swap(__float_as_uint(ps), __float_as_uint(ps), false, false); l_reg += __uint_as_float(rr[0]) + __uint_as_float(rr[1]); }
; }
; template <int NQ, int I> __device__ __forceinline__ void krd_pair(bf16x8& f0, bf16x8& f1, int ka, const int (&kb1)[2], const int (&kb2)[2]) {
.LBB0_395:
	s_add_i32 s6, s12, 1
	s_cmp_lt_i32 s12, 2
	s_cselect_b32 s19, s6, 0
	s_lshl_b32 s20, s19, 14
	v_add_u32_e32 v2, s20, v216
	ds_read_b128 v[6:9], v2
	ds_read_b128 v[2:5], v2 offset:8192
	v_max_f32_e32 v10, v129, v129
	v_max_f32_e32 v11, v128, v128
	v_max_f32_e32 v10, v11, v10
	v_max_f32_e32 v11, v112, v113
	v_max3_f32 v10, v10, v130, v131
	v_max3_f32 v11, v11, v114, v115
	v_max3_f32 v10, v10, v132, v133
	v_max3_f32 v11, v11, v116, v117
	v_max3_f32 v10, v10, v134, v135
	v_max3_f32 v11, v11, v118, v119
	v_max3_f32 v10, v10, v136, v137
	v_max3_f32 v11, v11, v120, v121
	v_max3_f32 v10, v10, v138, v139
	v_max3_f32 v11, v11, v122, v123
	v_max3_f32 v10, v10, v140, v141
	v_max3_f32 v11, v11, v124, v125
	v_max3_f32 v10, v10, v142, v143
	v_max3_f32 v11, v11, v126, v127
	v_max_f32_e32 v10, v10, v11
	v_mov_b32_e32 v11, v10
	s_nop 1
	v_permlane32_swap_b32_e32 v10, v11
	v_max_f32_e32 v10, v10, v11
	v_cmp_lt_f32_e32 vcc, s51, v10
	s_cmp_lg_u64 vcc, 0
	s_cselect_b64 s[12:13], -1, 0
	v_mov_b32_e32 v14, 1.0
	s_cbranch_vccnz .LBB0_409
.LBB0_397:
.LBB0_398:
	v_exp_f32_e32 v15, v128
	s_add_i32 s6, s16, 1
	s_cmp_lt_i32 s16, 3
	s_cselect_b32 s13, s6, 0
	v_exp_f32_e32 v180, v129
	v_exp_f32_e32 v181, v130
	v_exp_f32_e32 v182, v131
	v_exp_f32_e32 v183, v132
	v_exp_f32_e32 v200, v133
	v_exp_f32_e32 v201, v134
	v_exp_f32_e32 v202, v135
	v_exp_f32_e32 v203, v136
	v_exp_f32_e32 v204, v137
	v_exp_f32_e32 v205, v138
	v_exp_f32_e32 v206, v139
	v_exp_f32_e32 v207, v140
	v_exp_f32_e32 v208, v141
	v_exp_f32_e32 v209, v142
	v_exp_f32_e32 v210, v143
	s_waitcnt lgkmcnt(0)
	s_waitcnt lgkmcnt(0)
	v_add_u32_e32 v211, s20, v226
	v_add_u32_e32 v96, v211, v215
	ds_read_b128 v[10:13], v96 offset:0
	ds_read_b128 v[176:179], v96 offset:0x2000
	s_waitcnt lgkmcnt(2)
	v_mfma_f32_32x32x16_bf16 v[128:143], v[6:9], v[172:175], v[80:95]
	v_exp_f32_e32 v225, v112
	v_exp_f32_e32 v228, v113
	v_exp_f32_e32 v229, v114
	v_exp_f32_e32 v230, v115
	v_mfma_f32_32x32x16_bf16 v[96:111], v[2:5], v[172:175], v[80:95]
	v_add_u32_e32 v112, v211, v214
	ds_read_b128 v[2:5], v112 offset:0
	ds_read_b128 v[6:9], v112 offset:0x2000
	s_waitcnt lgkmcnt(2)
	v_mfma_f32_32x32x16_bf16 v[128:143], v[10:13], v[168:171], v[128:143]
	v_exp_f32_e32 v231, v116
	v_exp_f32_e32 v232, v117
	v_exp_f32_e32 v233, v118
	v_exp_f32_e32 v234, v119
	v_mfma_f32_32x32x16_bf16 v[96:111], v[176:179], v[168:171], v[96:111]
	v_add_u32_e32 v116, v211, v213
	ds_read_b128 v[10:13], v116 offset:0
	ds_read_b128 v[112:115], v116 offset:0x2000
	s_waitcnt lgkmcnt(2)
	v_mfma_f32_32x32x16_bf16 v[128:143], v[2:5], v[164:167], v[128:143]
	v_exp_f32_e32 v176, v120
	v_exp_f32_e32 v177, v121
	v_exp_f32_e32 v178, v122
	v_exp_f32_e32 v179, v123
	v_mfma_f32_32x32x16_bf16 v[96:111], v[6:9], v[164:167], v[96:111]
	v_add_u32_e32 v116, v211, v212
	ds_read_b128 v[2:5], v116 offset:0
	ds_read_b128 v[6:9], v116 offset:0x2000
	s_waitcnt lgkmcnt(2)
	v_mfma_f32_32x32x16_bf16 v[128:143], v[10:13], v[160:163], v[128:143]
	v_exp_f32_e32 v235, v124
	v_exp_f32_e32 v236, v125
	v_exp_f32_e32 v237, v126
	v_exp_f32_e32 v238, v127
	v_mfma_f32_32x32x16_bf16 v[96:111], v[112:115], v[160:163], v[96:111]
	v_add_u32_e32 v116, v211, v199
	ds_read_b128 v[10:13], v116 offset:0
	ds_read_b128 v[112:115], v116 offset:0x2000
	s_waitcnt lgkmcnt(2)
	v_mfma_f32_32x32x16_bf16 v[128:143], v[2:5], v[156:159], v[128:143]
	v_cvt_pk_bf16_f32 v2, v15, v180
	v_cvt_pk_bf16_f32 v3, v181, v182
	v_cvt_pk_bf16_f32 v4, v183, v200
	v_cvt_pk_bf16_f32 v5, v201, v202
	v_mfma_f32_32x32x16_bf16 v[96:111], v[6:9], v[156:159], v[96:111]
	v_add_f32_e32 v6, v180, v15
	v_add_f32_e32 v7, v182, v181
	v_add_f32_e32 v6, v7, v6
	v_add_f32_e32 v7, v200, v183
	v_add_f32_e32 v8, v202, v201
	v_add_f32_e32 v7, v8, v7
	v_add_f32_e32 v15, v7, v6
	v_add_u32_e32 v6, v211, v198
	ds_read_b128 v[116:119], v6 offset:0
	ds_read_b128 v[120:123], v6 offset:0x2000
	s_waitcnt lgkmcnt(2)
	v_mfma_f32_32x32x16_bf16 v[128:143], v[10:13], v[152:155], v[128:143]
	v_add_f32_e32 v10, v204, v203
	v_add_f32_e32 v11, v206, v205
	v_add_f32_e32 v10, v11, v10
	v_add_f32_e32 v11, v208, v207
	v_add_f32_e32 v12, v210, v209
	v_add_f32_e32 v11, v12, v11
	v_add_f32_e32 v10, v11, v10
	v_mfma_f32_32x32x16_bf16 v[96:111], v[112:115], v[152:155], v[96:111]
	v_add_f32_e32 v15, v10, v15
	v_cvt_pk_bf16_f32 v6, v203, v204
	v_cvt_pk_bf16_f32 v7, v205, v206
	v_cvt_pk_bf16_f32 v8, v207, v208
	v_cvt_pk_bf16_f32 v9, v209, v210
	v_add_u32_e32 v10, v211, v197
	ds_read_b128 v[112:115], v10 offset:0
	ds_read_b128 v[124:127], v10 offset:0x2000
	s_waitcnt lgkmcnt(2)
	v_mfma_f32_32x32x16_bf16 v[128:143], v[116:119], v[148:151], v[128:143]
	v_add_f32_e32 v116, v225, v228
	v_add_f32_e32 v117, v229, v230
	v_add_f32_e32 v116, v116, v117
	v_add_f32_e32 v117, v231, v232
	v_add_f32_e32 v118, v233, v234
	v_add_f32_e32 v117, v117, v118
	v_add_f32_e32 v116, v116, v117
	v_mfma_f32_32x32x16_bf16 v[96:111], v[120:123], v[148:151], v[96:111]
	v_add_f32_e32 v15, v15, v116
	v_cvt_pk_bf16_f32 v10, v225, v228
	v_cvt_pk_bf16_f32 v11, v229, v230
	v_cvt_pk_bf16_f32 v12, v231, v232
	v_cvt_pk_bf16_f32 v13, v233, v234
	s_waitcnt lgkmcnt(0)
	v_mfma_f32_32x32x16_bf16 v[128:143], v[112:115], v[144:147], v[128:143]
	v_add_f32_e32 v116, v176, v177
	v_add_f32_e32 v117, v178, v179
	v_add_f32_e32 v116, v116, v117
	v_add_f32_e32 v117, v235, v236
	v_add_f32_e32 v118, v237, v238
	v_add_f32_e32 v117, v117, v118
	v_add_f32_e32 v116, v116, v117
	v_mfma_f32_32x32x16_bf16 v[96:111], v[124:127], v[144:147], v[96:111]
	v_add_f32_e32 v15, v116, v15
	v_mov_b32_e32 v116, v15
	s_nop 1
	v_permlane32_swap_b32_e32 v15, v116
	v_cvt_pk_bf16_f32 v112, v176, v177
	v_cvt_pk_bf16_f32 v113, v178, v179
	v_cvt_pk_bf16_f32 v114, v235, v236
	v_cvt_pk_bf16_f32 v115, v237, v238
	s_and_b64 vcc, exec, s[8:9]
	s_cbranch_vccnz .LBB0_402
	s_cmpk_gt_u32 s18, 0xfb
	s_mov_b64 s[6:7], -1
	s_cbranch_scc1 .LBB0_428
	s_andn2_b64 vcc, exec, s[6:7]
	s_cbranch_vccnz .LBB0_402

; template <int MODE, bool FIRST, bool FOLD>
; __device__ __forceinline__ bool partialSM(f32x16& p0, f32x16& p1, float& m_reg, float& alpha, int relbase, bool near, const float* lut, float cb) {
;     ...
;     float pmax = p0[0];
; #pragma unroll
;     for (int r = 1; r < 16; ++r) pmax = fmaxf(pmax, p0[r]);
; #pragma unroll
;     for (int r = 0; r < 16; ++r) pmax = fmaxf(pmax, p1[r]);
;     { auto rr = __builtin_amdgcn_permlane32_swap(__float_as_uint(pmax), __float_as_uint(pmax), false, false);
;       pmax = fmaxf(__uint_as_float(rr[0]), __uint_as_float(rr[1])); }
;     bool resc;
;     if (FIRST && MODE != 2) resc = true; else resc = __any(pmax > THR2);
.LBB0_406:
	s_add_i32 s6, s19, 1
	s_cmp_lt_i32 s19, 2
	s_cselect_b32 s12, s6, 0
	s_lshl_b32 s19, s12, 14
	v_add_u32_e32 v2, s19, v216
	ds_read_b128 v[180:183], v2
	ds_read_b128 v[176:179], v2 offset:8192
	v_max_f32_e32 v2, v129, v129
	v_max_f32_e32 v3, v128, v128
	v_max_f32_e32 v2, v3, v2
	v_max_f32_e32 v3, v96, v97
	v_max3_f32 v2, v2, v130, v131
	v_max3_f32 v3, v3, v98, v99
	v_max3_f32 v2, v2, v132, v133
	v_max3_f32 v3, v3, v100, v101
	v_max3_f32 v2, v2, v134, v135
	v_max3_f32 v3, v3, v102, v103
	v_max3_f32 v2, v2, v136, v137
	v_max3_f32 v3, v3, v104, v105
	v_max3_f32 v2, v2, v138, v139
	v_max3_f32 v3, v3, v106, v107
	v_max3_f32 v2, v2, v140, v141
	v_max3_f32 v3, v3, v108, v109
	v_max3_f32 v2, v2, v142, v143
	v_max3_f32 v3, v3, v110, v111
	v_max_f32_e32 v2, v2, v3
	v_mov_b32_e32 v3, v2
	s_nop 1
	v_permlane32_swap_b32_e32 v2, v3
	v_max_f32_e32 v3, v2, v3
	v_cmp_lt_f32_e32 vcc, s51, v3
	s_cmp_lg_u64 vcc, 0
	s_cselect_b64 s[6:7], -1, 0
	v_mov_b32_e32 v2, 1.0
	s_cbranch_vccnz .LBB0_414

; template <int MODE, bool FIRST, bool FOLD>
; __device__ __forceinline__ bool partialSM(f32x16& p0, f32x16& p1, float& m_reg, float& alpha, int relbase, bool near, const float* lut, float cb) {
;     ...
;     float pmax = p0[0];
; #pragma unroll
;     for (int r = 1; r < 16; ++r) pmax = fmaxf(pmax, p0[r]);
; #pragma unroll
;     for (int r = 0; r < 16; ++r) pmax = fmaxf(pmax, p1[r]);
;     { auto rr = __builtin_amdgcn_permlane32_swap(__float_as_uint(pmax), __float_as_uint(pmax), false, false);
;       pmax = fmaxf(__uint_as_float(rr[0]), __uint_as_float(rr[1])); }
;     bool resc;
;     if (FIRST && MODE != 2) resc = true; else resc = __any(pmax > THR2);
; template <int NQ, int MODE> ...
;     ...
;     f32x16 cinit = f32x16{}; float cur_cb = 0.f; bool dirty = true;
.LBB0_711:
	s_add_i32 s37, s56, 0xffffff26
	s_sub_i32 s20, s56, 64
	s_cmp_gt_u32 s20, s25
	s_cselect_b64 s[20:21], -1, 0
	s_cmp_lt_u32 s37, s27
	s_cselect_b64 s[20:21], s[20:21], 0
	s_cmp_lt_u32 s37, s25
	s_cselect_b64 vcc, -1, 0
	v_cndmask_b32_e32 v14, v228, v227, vcc
	v_cndmask_b32_e64 v14, v14, 0, s[20:21]
	v_cmp_neq_f32_e64 s[38:39], v14, v242
	v_max_f32_e32 v0, v161, v161
	v_max_f32_e32 v10, v160, v160
	v_max_f32_e32 v0, v10, v0
	v_max_f32_e32 v10, v144, v145
	v_max3_f32 v0, v0, v162, v163
	v_max3_f32 v10, v10, v146, v147
	v_max3_f32 v0, v0, v164, v165
	v_max3_f32 v10, v10, v148, v149
	v_max3_f32 v0, v0, v166, v167
	v_max3_f32 v10, v10, v150, v151
	v_max3_f32 v0, v0, v168, v169
	v_max3_f32 v10, v10, v152, v153
	v_max3_f32 v0, v0, v170, v171
	v_max3_f32 v10, v10, v154, v155
	v_max3_f32 v0, v0, v172, v173
	v_max3_f32 v10, v10, v156, v157
	v_max3_f32 v0, v0, v174, v175
	v_max3_f32 v10, v10, v158, v159
	v_max_f32_e32 v0, v0, v10
	v_mov_b32_e32 v10, v0
	s_nop 1
	v_permlane32_swap_b32_e32 v0, v10
	v_max_f32_e32 v10, v0, v10
	v_cmp_lt_f32_e32 vcc, s51, v10
	s_cmp_lg_u64 vcc, 0
	s_cselect_b64 s[22:23], -1, 0
	v_mov_b32_e32 v0, 1.0
	s_cbranch_vccnz .LBB0_731
.LBB0_713:
	s_add_i32 s37, s56, 0xffffff26
	s_sub_i32 s20, s56, 64
	s_cmp_gt_u32 s20, s25
	s_cselect_b64 s[20:21], -1, 0
	s_cmp_lt_u32 s37, s27
	s_cselect_b64 s[20:21], s[20:21], 0
	s_or_b64 s[38:39], s[22:23], s[38:39]
	s_and_saveexec_b64 s[22:23], s[38:39]
	s_cbranch_execnz .LBB0_735

; template <int MODE, bool FIRST, bool FOLD>
; __device__ __forceinline__ bool partialSM(f32x16& p0, f32x16& p1, float& m_reg, float& alpha, int relbase, bool near, const float* lut, float cb) {
;     ...
;     float pmax = p0[0];
; #pragma unroll
;     for (int r = 1; r < 16; ++r) pmax = fmaxf(pmax, p0[r]);
; #pragma unroll
;     for (int r = 0; r < 16; ++r) pmax = fmaxf(pmax, p1[r]);
;     { auto rr = __builtin_amdgcn_permlane32_swap(__float_as_uint(pmax), __float_as_uint(pmax), false, false);
;       pmax = fmaxf(__uint_as_float(rr[0]), __uint_as_float(rr[1])); }
;     bool resc;
;     if (FIRST && MODE != 2) resc = true; else resc = __any(pmax > THR2);
; template <int NQ, int MODE> ...
;     ...
;     f32x16 cinit = f32x16{}; float cur_cb = 0.f; bool dirty = true;
.LBB0_726:
	s_add_i32 s78, s56, 0xffffff66
	s_cmp_gt_u32 s56, s25
	s_cselect_b64 s[22:23], -1, 0
	s_cmp_lt_u32 s78, s27
	s_cselect_b64 s[22:23], s[22:23], 0
	s_cmp_lt_u32 s78, s25
	s_cselect_b64 vcc, -1, 0
	v_cndmask_b32_e32 v244, v228, v227, vcc
	v_cndmask_b32_e64 v244, v244, 0, s[22:23]
	v_cmp_neq_f32_e64 s[38:39], v244, v242
	v_max_f32_e32 v2, v161, v161
	v_max_f32_e32 v3, v160, v160
	v_max_f32_e32 v2, v3, v2
	v_max_f32_e32 v3, v128, v129
	v_max3_f32 v2, v2, v162, v163
	v_max3_f32 v3, v3, v130, v131
	v_max3_f32 v2, v2, v164, v165
	v_max3_f32 v3, v3, v132, v133
	v_max3_f32 v2, v2, v166, v167
	v_max3_f32 v3, v3, v134, v135
	v_max3_f32 v2, v2, v168, v169
	v_max3_f32 v3, v3, v136, v137
	v_max3_f32 v2, v2, v170, v171
	v_max3_f32 v3, v3, v138, v139
	v_max3_f32 v2, v2, v172, v173
	v_max3_f32 v3, v3, v140, v141
	v_max3_f32 v2, v2, v174, v175
	v_max3_f32 v3, v3, v142, v143
	v_max_f32_e32 v2, v2, v3
	v_mov_b32_e32 v3, v2
	s_nop 1
	v_permlane32_swap_b32_e32 v2, v3
	v_max_f32_e32 v3, v2, v3
	v_cmp_lt_f32_e32 vcc, s51, v3
	s_cmp_lg_u64 vcc, 0
	s_cselect_b64 s[20:21], -1, 0
	v_mov_b32_e32 v2, 1.0
	s_cbranch_vccnz .LBB0_736
.LBB0_728:
	s_or_b64 s[22:23], s[20:21], s[38:39]
	s_and_saveexec_b64 s[20:21], s[22:23]
	s_cbranch_execnz .LBB0_740

.LBB0_735:
	v_sub_f32_e32 v112, v14, v238
	v_mov_b32_e32 v113, v112
	v_mov_b32_e32 v114, v112
	v_mov_b32_e32 v115, v112
	v_mov_b32_e32 v116, v112
	v_mov_b32_e32 v117, v112
	v_mov_b32_e32 v118, v112
	v_mov_b32_e32 v119, v112
	v_mov_b32_e32 v120, v112
	v_mov_b32_e32 v121, v112
	v_mov_b32_e32 v122, v112
	v_mov_b32_e32 v123, v112
	v_mov_b32_e32 v124, v112
	v_mov_b32_e32 v125, v112
	v_mov_b32_e32 v126, v112
	v_mov_b32_e32 v127, v112
	v_mov_b32_e32 v242, v14
	s_branch .LBB0_714

.LBB0_740:
	v_sub_f32_e32 v112, v244, v238
	v_mov_b32_e32 v113, v112
	v_mov_b32_e32 v114, v112
	v_mov_b32_e32 v115, v112
	v_mov_b32_e32 v116, v112
	v_mov_b32_e32 v117, v112
	v_mov_b32_e32 v118, v112
	v_mov_b32_e32 v119, v112
	v_mov_b32_e32 v120, v112
	v_mov_b32_e32 v121, v112
	v_mov_b32_e32 v122, v112
	v_mov_b32_e32 v123, v112
	v_mov_b32_e32 v124, v112
	v_mov_b32_e32 v125, v112
	v_mov_b32_e32 v126, v112
	v_mov_b32_e32 v127, v112
	v_mov_b32_e32 v242, v244
	s_branch .LBB0_729

; template <int MODE, bool FIRST, bool FOLD>
; __device__ __forceinline__ bool partialSM(f32x16& p0, f32x16& p1, float& m_reg, float& alpha, int relbase, bool near, const float* lut, float cb) {
;     ...
;     float pmax = p0[0];
; #pragma unroll
;     for (int r = 1; r < 16; ++r) pmax = fmaxf(pmax, p0[r]);
; #pragma unroll
;     for (int r = 0; r < 16; ++r) pmax = fmaxf(pmax, p1[r]);
;     { auto rr = __builtin_amdgcn_permlane32_swap(__float_as_uint(pmax), __float_as_uint(pmax), false, false);
;       pmax = fmaxf(__uint_as_float(rr[0]), __uint_as_float(rr[1])); }
;     bool resc;
;     if (FIRST && MODE != 2) resc = true; else resc = __any(pmax > THR2);
; template <int NQ, int MODE> ...
;     ...
;     f32x16 cinit = f32x16{}; float cur_cb = 0.f; bool dirty = true;
.LBB0_786:
	s_add_i32 s31, s16, 0xffffff26
	s_sub_i32 s12, s16, 64
	s_cmp_gt_u32 s12, s25
	s_cselect_b64 s[12:13], -1, 0
	s_cmp_lt_u32 s31, s27
	s_cselect_b64 s[12:13], s[12:13], 0
	s_cmp_lt_u32 s31, s25
	s_cselect_b64 vcc, -1, 0
	v_cndmask_b32_e32 v14, v228, v227, vcc
	v_cndmask_b32_e64 v14, v14, 0, s[12:13]
	v_cmp_neq_f32_e64 s[34:35], v14, v229
	v_max_f32_e32 v0, v145, v145
	v_max_f32_e32 v10, v144, v144
	v_max_f32_e32 v0, v10, v0
	v_max_f32_e32 v10, v128, v129
	v_max3_f32 v0, v0, v146, v147
	v_max3_f32 v10, v10, v130, v131
	v_max3_f32 v0, v0, v148, v149
	v_max3_f32 v10, v10, v132, v133
	v_max3_f32 v0, v0, v150, v151
	v_max3_f32 v10, v10, v134, v135
	v_max3_f32 v0, v0, v152, v153
	v_max3_f32 v10, v10, v136, v137
	v_max3_f32 v0, v0, v154, v155
	v_max3_f32 v10, v10, v138, v139
	v_max3_f32 v0, v0, v156, v157
	v_max3_f32 v10, v10, v140, v141
	v_max3_f32 v0, v0, v158, v159
	v_max3_f32 v10, v10, v142, v143
	v_max_f32_e32 v0, v0, v10
	v_mov_b32_e32 v10, v0
	s_nop 1
	v_permlane32_swap_b32_e32 v0, v10
	v_max_f32_e32 v10, v0, v10
	v_cmp_lt_f32_e32 vcc, s51, v10
	s_cmp_lg_u64 vcc, 0
	s_cselect_b64 s[14:15], -1, 0
	v_mov_b32_e32 v0, 1.0
	s_cbranch_vccnz .LBB0_806
.LBB0_788:
	s_add_i32 s31, s16, 0xffffff26
	s_sub_i32 s12, s16, 64
	s_cmp_gt_u32 s12, s25
	s_cselect_b64 s[12:13], -1, 0
	s_cmp_lt_u32 s31, s27
	s_cselect_b64 s[12:13], s[12:13], 0
	s_or_b64 s[34:35], s[14:15], s[34:35]
	s_and_saveexec_b64 s[14:15], s[34:35]
	s_cbranch_execnz .LBB0_810

; template <int MODE, bool FIRST, bool FOLD>
; __device__ __forceinline__ bool partialSM(f32x16& p0, f32x16& p1, float& m_reg, float& alpha, int relbase, bool near, const float* lut, float cb) {
;     ...
;     float pmax = p0[0];
; #pragma unroll
;     for (int r = 1; r < 16; ++r) pmax = fmaxf(pmax, p0[r]);
; #pragma unroll
;     for (int r = 0; r < 16; ++r) pmax = fmaxf(pmax, p1[r]);
;     { auto rr = __builtin_amdgcn_permlane32_swap(__float_as_uint(pmax), __float_as_uint(pmax), false, false);
;       pmax = fmaxf(__uint_as_float(rr[0]), __uint_as_float(rr[1])); }
;     bool resc;
;     if (FIRST && MODE != 2) resc = true; else resc = __any(pmax > THR2);
; template <int NQ, int MODE> ...
;     ...
;     f32x16 cinit = f32x16{}; float cur_cb = 0.f; bool dirty = true;
.LBB0_801:
	s_add_i32 s31, s16, 0xffffff66
	s_cmp_gt_u32 s16, s25
	s_cselect_b64 s[14:15], -1, 0
	s_cmp_lt_u32 s31, s27
	s_cselect_b64 s[14:15], s[14:15], 0
	s_cmp_lt_u32 s31, s25
	s_cselect_b64 vcc, -1, 0
	v_cndmask_b32_e32 v201, v228, v227, vcc
	v_cndmask_b32_e64 v201, v201, 0, s[14:15]
	v_cmp_neq_f32_e64 s[34:35], v201, v229
	v_max_f32_e32 v2, v145, v145
	v_max_f32_e32 v3, v144, v144
	v_max_f32_e32 v2, v3, v2
	v_max_f32_e32 v3, v112, v113
	v_max3_f32 v2, v2, v146, v147
	v_max3_f32 v3, v3, v114, v115
	v_max3_f32 v2, v2, v148, v149
	v_max3_f32 v3, v3, v116, v117
	v_max3_f32 v2, v2, v150, v151
	v_max3_f32 v3, v3, v118, v119
	v_max3_f32 v2, v2, v152, v153
	v_max3_f32 v3, v3, v120, v121
	v_max3_f32 v2, v2, v154, v155
	v_max3_f32 v3, v3, v122, v123
	v_max3_f32 v2, v2, v156, v157
	v_max3_f32 v3, v3, v124, v125
	v_max3_f32 v2, v2, v158, v159
	v_max3_f32 v3, v3, v126, v127
	v_max_f32_e32 v2, v2, v3
	v_mov_b32_e32 v3, v2
	s_nop 1
	v_permlane32_swap_b32_e32 v2, v3
	v_max_f32_e32 v3, v2, v3
	v_cmp_lt_f32_e32 vcc, s51, v3
	s_cmp_lg_u64 vcc, 0
	s_cselect_b64 s[12:13], -1, 0
	v_mov_b32_e32 v2, 1.0
	s_cbranch_vccnz .LBB0_811
.LBB0_803:
	s_or_b64 s[14:15], s[12:13], s[34:35]
	s_and_saveexec_b64 s[12:13], s[14:15]
	s_cbranch_execnz .LBB0_815

.LBB0_810:
	v_sub_f32_e32 v96, v14, v199
	v_mov_b32_e32 v97, v96
	v_mov_b32_e32 v98, v96
	v_mov_b32_e32 v99, v96
	v_mov_b32_e32 v100, v96
	v_mov_b32_e32 v101, v96
	v_mov_b32_e32 v102, v96
	v_mov_b32_e32 v103, v96
	v_mov_b32_e32 v104, v96
	v_mov_b32_e32 v105, v96
	v_mov_b32_e32 v106, v96
	v_mov_b32_e32 v107, v96
	v_mov_b32_e32 v108, v96
	v_mov_b32_e32 v109, v96
	v_mov_b32_e32 v110, v96
	v_mov_b32_e32 v111, v96
	v_mov_b32_e32 v229, v14
	s_branch .LBB0_789

.LBB0_815:
	v_sub_f32_e32 v96, v201, v199
	v_mov_b32_e32 v97, v96
	v_mov_b32_e32 v98, v96
	v_mov_b32_e32 v99, v96
	v_mov_b32_e32 v100, v96
	v_mov_b32_e32 v101, v96
	v_mov_b32_e32 v102, v96
	v_mov_b32_e32 v103, v96
	v_mov_b32_e32 v104, v96
	v_mov_b32_e32 v105, v96
	v_mov_b32_e32 v106, v96
	v_mov_b32_e32 v107, v96
	v_mov_b32_e32 v108, v96
	v_mov_b32_e32 v109, v96
	v_mov_b32_e32 v110, v96
	v_mov_b32_e32 v111, v96
	v_mov_b32_e32 v229, v201
	s_branch .LBB0_804
